# postA row loop: three contiguous 30-instruction 1/sqrtf expansions replaced by v_rsq_f32 + one Newton step (on top of the packed up-GEMM epilogue)
# baseline (speedup 1.0000x reference)
.LBB0_371:
	s_waitcnt vmcnt(0)
	v_lshlrev_b32_e32 v78, 16, v74
	v_and_b32_e32 v79, 0xffff0000, v74
	v_pk_mul_f32 v[80:81], v[78:79], v[78:79]
	v_lshlrev_b32_e32 v84, 16, v75
	v_and_b32_e32 v85, 0xffff0000, v75
	v_pk_mul_f32 v[86:87], v[84:85], v[84:85]
	v_add_f32_e32 v3, v80, v81
	v_lshlrev_b32_e32 v88, 16, v76
	v_and_b32_e32 v89, 0xffff0000, v76
	v_add_f32_e32 v3, v86, v3
	v_pk_mul_f32 v[90:91], v[88:89], v[88:89]
	v_add_f32_e32 v3, v87, v3
	v_lshlrev_b32_e32 v92, 16, v77
	v_and_b32_e32 v93, 0xffff0000, v77
	v_add_f32_e32 v3, v90, v3
	v_pk_mul_f32 v[94:95], v[92:93], v[92:93]
	v_add_f32_e32 v3, v91, v3
	v_add_f32_e32 v3, v94, v3
	v_add_f32_e32 v3, v95, v3
	ds_bpermute_b32 v5, v147, v3
	s_waitcnt lgkmcnt(0)
	v_add_f32_e32 v3, v3, v5
	ds_bpermute_b32 v5, v148, v3
	s_waitcnt lgkmcnt(0)
	v_add_f32_e32 v3, v3, v5
	ds_bpermute_b32 v5, v149, v3
	s_waitcnt lgkmcnt(0)
	v_add_f32_e32 v3, v3, v5
	ds_bpermute_b32 v5, v150, v3
	s_waitcnt lgkmcnt(0)
	v_add_f32_e32 v3, v3, v5
	v_fmamk_f32 v3, v3, 0x3c000000, v224
	v_rsq_f32_e32 v5, v3
	s_nop 0
	v_mul_f32_e32 v7, v3, v5
	v_mul_f32_e32 v7, v7, v5
	v_fmaak_f32 v7, -0.5, v7, 0x3fc00000
	v_mul_f32_e32 v86, v5, v7
	v_pk_mul_f32 v[78:79], v[86:87], v[78:79] op_sel_hi:[0,1]
	v_pk_mul_f32 v[84:85], v[86:87], v[84:85] op_sel_hi:[0,1]
	v_pk_mul_f32 v[80:81], v[54:55], v[78:79]
	v_pk_mul_f32 v[78:79], v[56:57], v[84:85]
	v_pk_mul_f32 v[84:85], v[86:87], v[88:89] op_sel_hi:[0,1]
	v_pk_mul_f32 v[86:87], v[86:87], v[92:93] op_sel_hi:[0,1]
	v_cndmask_b32_e64 v3, 0, 1, s[20:21]
	v_pk_mul_f32 v[84:85], v[50:51], v[84:85]
	v_cmp_ne_u32_e64 s[46:47], 1, v3
	s_andn2_b64 vcc, exec, s[20:21]
	v_pk_mul_f32 v[86:87], v[52:53], v[86:87]
	s_cbranch_vccnz .LBB0_373
	ds_bpermute_b32 v88, v149, v80
	ds_bpermute_b32 v89, v149, v81
	v_mov_b32_e32 v92, v59
	v_mov_b32_e32 v93, v61
	v_mov_b32_e32 v90, v58
	v_mov_b32_e32 v91, v60
	s_waitcnt lgkmcnt(0)
	v_pk_mul_f32 v[88:89], v[92:93], v[88:89]
	v_mov_b32_e32 v92, v63
	v_cndmask_b32_e64 v89, v89, -v89, s[42:43]
	v_cndmask_b32_e64 v88, v88, -v88, s[42:43]
	v_pk_fma_f32 v[80:81], v[90:91], v[80:81], v[88:89]
	ds_bpermute_b32 v88, v149, v78
	ds_bpermute_b32 v89, v149, v79
	v_mov_b32_e32 v93, v65
	v_mov_b32_e32 v90, v62
	v_mov_b32_e32 v91, v64
	s_waitcnt lgkmcnt(0)
	v_pk_mul_f32 v[88:89], v[92:93], v[88:89]
	s_nop 0
	v_cndmask_b32_e64 v89, v89, -v89, s[42:43]
	v_cndmask_b32_e64 v88, v88, -v88, s[42:43]
	v_pk_fma_f32 v[78:79], v[90:91], v[78:79], v[88:89]
	ds_bpermute_b32 v88, v149, v84
	ds_bpermute_b32 v89, v149, v85
	v_mov_b32_e32 v92, v67
	v_mov_b32_e32 v93, v69
	v_mov_b32_e32 v90, v66
	v_mov_b32_e32 v91, v68
	s_waitcnt lgkmcnt(0)
	v_pk_mul_f32 v[88:89], v[92:93], v[88:89]
	v_mov_b32_e32 v92, v71
	v_cndmask_b32_e64 v89, v89, -v89, s[42:43]
	v_cndmask_b32_e64 v88, v88, -v88, s[42:43]
	v_pk_fma_f32 v[84:85], v[90:91], v[84:85], v[88:89]
	ds_bpermute_b32 v88, v149, v86
	ds_bpermute_b32 v89, v149, v87
	v_mov_b32_e32 v93, v73
	v_mov_b32_e32 v90, v70
	v_mov_b32_e32 v91, v72
	s_waitcnt lgkmcnt(0)
	v_pk_mul_f32 v[88:89], v[92:93], v[88:89]
	s_nop 0
	v_cndmask_b32_e64 v89, v89, -v89, s[42:43]
	v_cndmask_b32_e64 v88, v88, -v88, s[42:43]
	v_pk_fma_f32 v[86:87], v[90:91], v[86:87], v[88:89]

.LBB0_378:
	v_add_co_u32_e32 v78, vcc, 0x21e24000, v82
	s_and_b64 s[8:9], exec, s[48:49]
	s_nop 0
	v_addc_co_u32_e32 v79, vcc, 0, v83, vcc
	global_load_dwordx4 v[136:139], v[78:79], off
	s_mov_b32 s7, 0x21e26000
	v_add_co_u32_e32 v84, vcc, s7, v82
	s_movk_i32 s7, 0xfff
	s_cselect_b32 s5, s6, s5
	s_cselect_b32 s8, 0xff, s7
	s_cmp_eq_u32 s5, 0
	s_cselect_b64 s[70:71], -1, 0
	s_and_b64 s[6:7], s[70:71], exec
	v_addc_co_u32_e32 v85, vcc, 0, v83, vcc
	s_cselect_b32 s6, 0, 0xffffd800
	s_cselect_b32 s7, 0, -1
	s_cmp_lt_u32 s5, s8
	v_add_co_u32_e32 v86, vcc, 0x21e25000, v82
	s_cselect_b64 s[72:73], -1, 0
	s_nop 0
	v_addc_co_u32_e32 v87, vcc, 0, v83, vcc
	v_lshl_add_u64 v[88:89], v[82:83], 0, s[6:7]
	s_and_b64 s[6:7], s[72:73], exec
	s_mov_b32 s5, 0x21e25000
	v_add_co_u32_e32 v94, vcc, s5, v88
	s_cselect_b32 s52, 0x2800, 0
	s_nop 0
	v_addc_co_u32_e32 v95, vcc, 0, v89, vcc
	v_lshl_add_u64 v[82:83], v[82:83], 0, s[52:53]
	v_add_co_u32_e32 v82, vcc, s5, v82
	global_load_dwordx4 v[74:77], v[84:85], off offset:1024
	global_load_dwordx4 v[112:115], v[78:79], off offset:1024
	v_addc_co_u32_e32 v83, vcc, 0, v83, vcc
	global_load_dwordx4 v[100:103], v[86:87], off offset:1024
	global_load_dwordx4 v[78:81], v[86:87], off offset:2048
	s_nop 0
	global_load_dwordx4 v[86:89], v[86:87], off offset:3072
	s_nop 0
	global_load_dwordx4 v[90:93], v[94:95], off offset:2048
	s_nop 0
	global_load_dwordx4 v[94:97], v[94:95], off offset:3072
	s_nop 0
	global_load_dwordx4 v[108:111], v[82:83], off offset:2048
	global_load_dwordx4 v[104:107], v[82:83], off offset:3072
	s_nop 0
	global_load_dwordx4 v[82:85], v[84:85], off
	s_waitcnt vmcnt(10)
	v_lshlrev_b32_e32 v142, 16, v136
	v_and_b32_e32 v143, 0xffff0000, v136
	v_lshlrev_b32_e32 v136, 16, v137
	v_and_b32_e32 v137, 0xffff0000, v137
	v_pk_mul_f32 v[156:157], v[142:143], v[142:143]
	v_pk_mul_f32 v[158:159], v[136:137], v[136:137]
	v_add_f32_e32 v3, v156, v157
	v_lshlrev_b32_e32 v154, 16, v138
	v_and_b32_e32 v155, 0xffff0000, v138
	v_add_f32_e32 v3, v158, v3
	v_pk_mul_f32 v[160:161], v[154:155], v[154:155]
	v_add_f32_e32 v3, v159, v3
	v_and_b32_e32 v140, 0xffff0000, v139
	v_lshlrev_b32_e32 v141, 16, v139
	v_add_f32_e32 v3, v160, v3
	v_pk_mul_f32 v[138:139], v[140:141], v[140:141]
	v_add_f32_e32 v3, v161, v3
	v_add_f32_e32 v3, v139, v3
	v_add_f32_e32 v3, v138, v3
	ds_bpermute_b32 v5, v147, v3
	s_waitcnt lgkmcnt(0)
	v_add_f32_e32 v3, v3, v5
	ds_bpermute_b32 v5, v148, v3
	s_waitcnt lgkmcnt(0)
	v_add_f32_e32 v3, v3, v5
	ds_bpermute_b32 v5, v149, v3
	s_waitcnt lgkmcnt(0)
	v_add_f32_e32 v3, v3, v5
	ds_bpermute_b32 v5, v150, v3
	s_waitcnt lgkmcnt(0)
	v_add_f32_e32 v3, v3, v5
	v_fmamk_f32 v3, v3, 0x3c000000, v224
	v_rsq_f32_e32 v5, v3
	s_nop 0
	v_mul_f32_e32 v7, v3, v5
	v_mul_f32_e32 v7, v7, v5
	v_fmaak_f32 v7, -0.5, v7, 0x3fc00000
	v_mul_f32_e32 v138, v5, v7
	v_pk_mul_f32 v[142:143], v[138:139], v[142:143] op_sel_hi:[0,1]
	v_pk_mul_f32 v[156:157], v[138:139], v[136:137] op_sel_hi:[0,1]
	v_pk_mul_f32 v[154:155], v[138:139], v[154:155] op_sel_hi:[0,1]
	v_pk_mul_f32 v[158:159], v[138:139], v[140:141] op_sel_hi:[0,1]
	s_and_b64 vcc, exec, s[46:47]
	v_pk_mul_f32 v[136:137], v[46:47], v[142:143]
	v_pk_mul_f32 v[138:139], v[48:49], v[156:157]
	v_pk_mul_f32 v[140:141], v[42:43], v[154:155]
	v_pk_mul_f32 v[142:143], v[44:45], v[158:159] op_sel:[0,1] op_sel_hi:[1,0]
	s_cbranch_vccnz .LBB0_380
	ds_bpermute_b32 v154, v149, v136
	ds_bpermute_b32 v155, v149, v137
	v_mov_b32_e32 v158, v59
	v_mov_b32_e32 v159, v61
	v_mov_b32_e32 v156, v58
	v_mov_b32_e32 v157, v60
	s_waitcnt lgkmcnt(0)
	v_pk_mul_f32 v[154:155], v[158:159], v[154:155]
	v_mov_b32_e32 v158, v63
	v_cndmask_b32_e64 v155, v155, -v155, s[42:43]
	v_cndmask_b32_e64 v154, v154, -v154, s[42:43]
	v_pk_fma_f32 v[136:137], v[156:157], v[136:137], v[154:155]
	ds_bpermute_b32 v154, v149, v138
	ds_bpermute_b32 v155, v149, v139
	v_mov_b32_e32 v159, v65
	v_mov_b32_e32 v156, v62
	v_mov_b32_e32 v157, v64
	s_waitcnt lgkmcnt(0)
	v_pk_mul_f32 v[154:155], v[158:159], v[154:155]
	s_nop 0
	v_cndmask_b32_e64 v155, v155, -v155, s[42:43]
	v_cndmask_b32_e64 v154, v154, -v154, s[42:43]
	v_pk_fma_f32 v[138:139], v[156:157], v[138:139], v[154:155]
	ds_bpermute_b32 v154, v149, v140
	ds_bpermute_b32 v155, v149, v141
	v_mov_b32_e32 v158, v67
	v_mov_b32_e32 v159, v69
	v_mov_b32_e32 v156, v66
	v_mov_b32_e32 v157, v68
	s_waitcnt lgkmcnt(0)
	v_pk_mul_f32 v[154:155], v[158:159], v[154:155]
	v_mov_b32_e32 v158, v71
	v_cndmask_b32_e64 v155, v155, -v155, s[42:43]
	v_cndmask_b32_e64 v154, v154, -v154, s[42:43]
	v_pk_fma_f32 v[140:141], v[156:157], v[140:141], v[154:155]
	ds_bpermute_b32 v154, v149, v142
	ds_bpermute_b32 v155, v149, v143
	v_mov_b32_e32 v159, v73
	v_mov_b32_e32 v156, v70
	v_mov_b32_e32 v157, v72
	s_waitcnt lgkmcnt(0)
	v_pk_mul_f32 v[154:155], v[158:159], v[154:155]
	s_nop 0
	v_cndmask_b32_e64 v155, v155, -v155, s[42:43]
	v_cndmask_b32_e64 v154, v154, -v154, s[42:43]
	v_pk_fma_f32 v[142:143], v[156:157], v[142:143], v[154:155]
.LBB0_380:
	v_lshl_add_u64 v[158:159], s[64:65], 0, v[98:99]
	s_mov_b32 s5, 0x35024000
	v_cvt_pk_bf16_f32 v154, v136, v137
	v_add_co_u32_e32 v136, vcc, s5, v158
	v_cvt_pk_bf16_f32 v155, v138, v139
	v_cvt_pk_bf16_f32 v156, v140, v141
	s_waitcnt vmcnt(8)
	v_lshlrev_b32_e32 v140, 16, v112
	v_addc_co_u32_e32 v137, vcc, 0, v159, vcc
	v_and_b32_e32 v141, 0xffff0000, v112
	v_cvt_pk_bf16_f32 v157, v142, v143
	global_store_dwordx4 v[136:137], v[154:157], off
	v_lshlrev_b32_e32 v112, 16, v113
	v_and_b32_e32 v113, 0xffff0000, v113
	v_pk_mul_f32 v[154:155], v[140:141], v[140:141]
	v_pk_mul_f32 v[156:157], v[112:113], v[112:113]
	v_add_f32_e32 v3, v154, v155
	v_lshlrev_b32_e32 v158, 16, v114
	v_and_b32_e32 v159, 0xffff0000, v114
	v_add_f32_e32 v3, v156, v3
	v_and_b32_e32 v142, 0xffff0000, v115
	v_lshlrev_b32_e32 v143, 16, v115
	v_pk_mul_f32 v[114:115], v[158:159], v[158:159]
	v_add_f32_e32 v3, v157, v3
	v_add_f32_e32 v3, v114, v3
	v_pk_mul_f32 v[138:139], v[142:143], v[142:143]
	v_add_f32_e32 v3, v115, v3
	v_add_f32_e32 v3, v139, v3
	v_add_f32_e32 v3, v138, v3
	ds_bpermute_b32 v5, v147, v3
	s_waitcnt lgkmcnt(0)
	v_add_f32_e32 v3, v3, v5
	ds_bpermute_b32 v5, v148, v3
	s_waitcnt lgkmcnt(0)
	v_add_f32_e32 v3, v3, v5
	ds_bpermute_b32 v5, v149, v3
	s_waitcnt lgkmcnt(0)
	v_add_f32_e32 v3, v3, v5
	ds_bpermute_b32 v5, v150, v3
	s_waitcnt lgkmcnt(0)
	v_add_f32_e32 v3, v3, v5
	v_fmamk_f32 v3, v3, 0x3c000000, v224
	v_rsq_f32_e32 v5, v3
	s_nop 0
	v_mul_f32_e32 v7, v3, v5
	v_mul_f32_e32 v7, v7, v5
	v_fmaak_f32 v7, -0.5, v7, 0x3fc00000
	v_mul_f32_e32 v154, v5, v7
	v_pk_mul_f32 v[112:113], v[154:155], v[112:113] op_sel_hi:[0,1]
	v_pk_mul_f32 v[114:115], v[154:155], v[140:141] op_sel_hi:[0,1]
	v_pk_mul_f32 v[138:139], v[48:49], v[112:113]
	v_pk_mul_f32 v[112:113], v[154:155], v[158:159] op_sel_hi:[0,1]
	v_pk_mul_f32 v[140:141], v[46:47], v[114:115]
	v_pk_mul_f32 v[114:115], v[42:43], v[112:113]
	v_pk_mul_f32 v[112:113], v[154:155], v[142:143] op_sel_hi:[0,1]
	v_pk_mul_f32 v[112:113], v[44:45], v[112:113] op_sel:[0,1] op_sel_hi:[1,0]
	s_and_b64 vcc, exec, s[46:47]
	s_cbranch_vccnz .LBB0_367
	ds_bpermute_b32 v142, v149, v140
	ds_bpermute_b32 v143, v149, v141
	v_mov_b32_e32 v156, v59
	v_mov_b32_e32 v157, v61
	v_mov_b32_e32 v154, v58
	v_mov_b32_e32 v155, v60
	s_waitcnt lgkmcnt(0)
	v_pk_mul_f32 v[142:143], v[156:157], v[142:143]
	v_mov_b32_e32 v156, v63
	v_cndmask_b32_e64 v143, v143, -v143, s[42:43]
	v_cndmask_b32_e64 v142, v142, -v142, s[42:43]
	v_pk_fma_f32 v[140:141], v[154:155], v[140:141], v[142:143]
	ds_bpermute_b32 v142, v149, v138
	ds_bpermute_b32 v143, v149, v139
	v_mov_b32_e32 v157, v65
	v_mov_b32_e32 v154, v62
	v_mov_b32_e32 v155, v64
	s_waitcnt lgkmcnt(0)
	v_pk_mul_f32 v[142:143], v[156:157], v[142:143]
	s_nop 0
	v_cndmask_b32_e64 v143, v143, -v143, s[42:43]
	v_cndmask_b32_e64 v142, v142, -v142, s[42:43]
	v_pk_fma_f32 v[138:139], v[154:155], v[138:139], v[142:143]
	ds_bpermute_b32 v142, v149, v114
	ds_bpermute_b32 v143, v149, v115
	v_mov_b32_e32 v156, v67
	v_mov_b32_e32 v157, v69
	v_mov_b32_e32 v154, v66
	v_mov_b32_e32 v155, v68
	s_waitcnt lgkmcnt(0)
	v_pk_mul_f32 v[142:143], v[156:157], v[142:143]
	v_mov_b32_e32 v156, v71
	v_cndmask_b32_e64 v143, v143, -v143, s[42:43]
	v_cndmask_b32_e64 v142, v142, -v142, s[42:43]
	v_pk_fma_f32 v[114:115], v[154:155], v[114:115], v[142:143]
	ds_bpermute_b32 v142, v149, v112
	ds_bpermute_b32 v143, v149, v113
	v_mov_b32_e32 v157, v73
	v_mov_b32_e32 v154, v70
	v_mov_b32_e32 v155, v72
	s_waitcnt lgkmcnt(0)
	v_pk_mul_f32 v[142:143], v[156:157], v[142:143]
	s_nop 0
	v_cndmask_b32_e64 v143, v143, -v143, s[42:43]
	v_cndmask_b32_e64 v142, v142, -v142, s[42:43]
	v_pk_fma_f32 v[112:113], v[154:155], v[112:113], v[142:143]
	s_branch .LBB0_367
